# FFN-up SwiGLU epilogue regenerated with packed-f32 VALU (v_pk_mul/v_pk_add, bit-identical arithmetic order), staged 4 pairs at a time
# speedup vs baseline: 1.0212x; 1.0040x over previous
.LBB0_603:
	v_mov_b64_e32 v[136:137], s[24:25]
	s_movk_i32 s16, 0x2b00
	v_mov_b32_e32 v196, 0xbfb8aa3b
	v_mad_u64_u32 v[172:173], s[4:5], v170, s16, v[136:137]
	v_lshl_or_b32 v138, s20, 7, v183
	v_mov_b32_e32 v170, v173
	v_ashrrev_i32_e32 v139, 31, v138
	v_mad_u64_u32 v[170:171], s[4:5], v171, s16, v[170:171]
	v_mov_b32_e32 v173, v170
	v_lshlrev_b64 v[138:139], 1, v[138:139]
	v_lshl_add_u64 v[170:171], v[172:173], 0, v[138:139]
	s_andn2_b64 vcc, exec, s[6:7]
	v_pk_mul_f32 v[206:207], v[6:7], v[174:175] op_sel_hi:[1,0]
	v_pk_mul_f32 v[208:209], v[8:9], v[174:175] op_sel_hi:[1,0]
	v_pk_mul_f32 v[210:211], v[130:131], v[174:175] op_sel_hi:[1,0]
	v_pk_mul_f32 v[212:213], v[132:133], v[174:175] op_sel_hi:[1,0]
	v_pk_mul_f32 v[214:215], v[206:207], v[196:197] op_sel_hi:[1,0]
	v_pk_mul_f32 v[216:217], v[208:209], v[196:197] op_sel_hi:[1,0]
	v_pk_mul_f32 v[218:219], v[210:211], v[196:197] op_sel_hi:[1,0]
	v_pk_mul_f32 v[220:221], v[212:213], v[196:197] op_sel_hi:[1,0]
	v_exp_f32_e32 v214, v214
	v_exp_f32_e32 v215, v215
	v_exp_f32_e32 v216, v216
	v_exp_f32_e32 v217, v217
	v_exp_f32_e32 v218, v218
	v_exp_f32_e32 v219, v219
	v_exp_f32_e32 v220, v220
	v_exp_f32_e32 v221, v221
	v_pk_add_f32 v[214:215], v[214:215], 1.0 op_sel_hi:[1,0]
	v_pk_add_f32 v[216:217], v[216:217], 1.0 op_sel_hi:[1,0]
	v_pk_add_f32 v[218:219], v[218:219], 1.0 op_sel_hi:[1,0]
	v_pk_add_f32 v[220:221], v[220:221], 1.0 op_sel_hi:[1,0]
	v_rcp_f32_e32 v214, v214
	v_rcp_f32_e32 v215, v215
	v_rcp_f32_e32 v216, v216
	v_rcp_f32_e32 v217, v217
	v_rcp_f32_e32 v218, v218
	v_rcp_f32_e32 v219, v219
	v_rcp_f32_e32 v220, v220
	v_rcp_f32_e32 v221, v221
	v_pk_mul_f32 v[214:215], v[206:207], v[214:215]
	v_pk_mul_f32 v[216:217], v[208:209], v[216:217]
	v_pk_mul_f32 v[218:219], v[210:211], v[218:219]
	v_pk_mul_f32 v[220:221], v[212:213], v[220:221]
	v_pk_mul_f32 v[206:207], v[102:103], v[174:175] op_sel_hi:[1,0]
	v_pk_mul_f32 v[208:209], v[104:105], v[174:175] op_sel_hi:[1,0]
	v_pk_mul_f32 v[210:211], v[98:99], v[174:175] op_sel_hi:[1,0]
	v_pk_mul_f32 v[212:213], v[100:101], v[174:175] op_sel_hi:[1,0]
	v_pk_mul_f32 v[214:215], v[206:207], v[214:215]
	v_pk_mul_f32 v[216:217], v[208:209], v[216:217]
	v_pk_mul_f32 v[218:219], v[210:211], v[218:219]
	v_pk_mul_f32 v[220:221], v[212:213], v[220:221]
	v_cvt_pk_bf16_f32 v224, v214, v215
	v_cvt_pk_bf16_f32 v225, v216, v217
	v_cvt_pk_bf16_f32 v226, v218, v219
	v_cvt_pk_bf16_f32 v227, v220, v221
	flat_store_dwordx4 v[170:171], v[224:227]
	v_mad_u64_u32 v[170:171], s[4:5], v164, s16, v[136:137]
	v_mov_b32_e32 v164, v171
	v_mad_u64_u32 v[164:165], s[4:5], v165, s16, v[164:165]
	v_mov_b32_e32 v171, v164
	v_lshl_add_u64 v[164:165], v[170:171], 0, v[138:139]
	v_pk_mul_f32 v[232:233], v[126:127], v[168:169] op_sel_hi:[1,0]
	v_pk_mul_f32 v[234:235], v[128:129], v[168:169] op_sel_hi:[1,0]
	v_pk_mul_f32 v[236:237], v[122:123], v[168:169] op_sel_hi:[1,0]
	v_pk_mul_f32 v[240:241], v[124:125], v[168:169] op_sel_hi:[1,0]
	v_pk_mul_f32 v[242:243], v[232:233], v[196:197] op_sel_hi:[1,0]
	v_pk_mul_f32 v[244:245], v[234:235], v[196:197] op_sel_hi:[1,0]
	v_pk_mul_f32 v[248:249], v[236:237], v[196:197] op_sel_hi:[1,0]
	v_pk_mul_f32 v[200:201], v[240:241], v[196:197] op_sel_hi:[1,0]
	v_exp_f32_e32 v242, v242
	v_exp_f32_e32 v243, v243
	v_exp_f32_e32 v244, v244
	v_exp_f32_e32 v245, v245
	v_exp_f32_e32 v248, v248
	v_exp_f32_e32 v249, v249
	v_exp_f32_e32 v200, v200
	v_exp_f32_e32 v201, v201
	v_pk_add_f32 v[242:243], v[242:243], 1.0 op_sel_hi:[1,0]
	v_pk_add_f32 v[244:245], v[244:245], 1.0 op_sel_hi:[1,0]
	v_pk_add_f32 v[248:249], v[248:249], 1.0 op_sel_hi:[1,0]
	v_pk_add_f32 v[200:201], v[200:201], 1.0 op_sel_hi:[1,0]
	v_rcp_f32_e32 v242, v242
	v_rcp_f32_e32 v243, v243
	v_rcp_f32_e32 v244, v244
	v_rcp_f32_e32 v245, v245
	v_rcp_f32_e32 v248, v248
	v_rcp_f32_e32 v249, v249
	v_rcp_f32_e32 v200, v200
	v_rcp_f32_e32 v201, v201
	v_pk_mul_f32 v[242:243], v[232:233], v[242:243]
	v_pk_mul_f32 v[244:245], v[234:235], v[244:245]
	v_pk_mul_f32 v[248:249], v[236:237], v[248:249]
	v_pk_mul_f32 v[200:201], v[240:241], v[200:201]
	v_pk_mul_f32 v[232:233], v[94:95], v[168:169] op_sel_hi:[1,0]
	v_pk_mul_f32 v[234:235], v[96:97], v[168:169] op_sel_hi:[1,0]
	v_pk_mul_f32 v[236:237], v[90:91], v[168:169] op_sel_hi:[1,0]
	v_pk_mul_f32 v[240:241], v[92:93], v[168:169] op_sel_hi:[1,0]
	v_pk_mul_f32 v[242:243], v[232:233], v[242:243]
	v_pk_mul_f32 v[244:245], v[234:235], v[244:245]
	v_pk_mul_f32 v[248:249], v[236:237], v[248:249]
	v_pk_mul_f32 v[200:201], v[240:241], v[200:201]
	v_cvt_pk_bf16_f32 v228, v242, v243
	v_cvt_pk_bf16_f32 v229, v244, v245
	v_cvt_pk_bf16_f32 v230, v248, v249
	v_cvt_pk_bf16_f32 v231, v200, v201
	flat_store_dwordx4 v[164:165], v[228:231]
	v_mad_u64_u32 v[164:165], s[4:5], v158, s16, v[136:137]
	v_mov_b32_e32 v158, v165
	v_mad_u64_u32 v[158:159], s[4:5], v159, s16, v[158:159]
	v_mov_b32_e32 v165, v158
	v_lshl_add_u64 v[158:159], v[164:165], 0, v[138:139]
	v_pk_mul_f32 v[206:207], v[118:119], v[166:167] op_sel_hi:[1,0]
	v_pk_mul_f32 v[208:209], v[120:121], v[166:167] op_sel_hi:[1,0]
	v_pk_mul_f32 v[210:211], v[114:115], v[166:167] op_sel_hi:[1,0]
	v_pk_mul_f32 v[212:213], v[116:117], v[166:167] op_sel_hi:[1,0]
	v_pk_mul_f32 v[214:215], v[206:207], v[196:197] op_sel_hi:[1,0]
	v_pk_mul_f32 v[216:217], v[208:209], v[196:197] op_sel_hi:[1,0]
	v_pk_mul_f32 v[218:219], v[210:211], v[196:197] op_sel_hi:[1,0]
	v_pk_mul_f32 v[220:221], v[212:213], v[196:197] op_sel_hi:[1,0]
	v_exp_f32_e32 v214, v214
	v_exp_f32_e32 v215, v215
	v_exp_f32_e32 v216, v216
	v_exp_f32_e32 v217, v217
	v_exp_f32_e32 v218, v218
	v_exp_f32_e32 v219, v219
	v_exp_f32_e32 v220, v220
	v_exp_f32_e32 v221, v221
	v_pk_add_f32 v[214:215], v[214:215], 1.0 op_sel_hi:[1,0]
	v_pk_add_f32 v[216:217], v[216:217], 1.0 op_sel_hi:[1,0]
	v_pk_add_f32 v[218:219], v[218:219], 1.0 op_sel_hi:[1,0]
	v_pk_add_f32 v[220:221], v[220:221], 1.0 op_sel_hi:[1,0]
	v_rcp_f32_e32 v214, v214
	v_rcp_f32_e32 v215, v215
	v_rcp_f32_e32 v216, v216
	v_rcp_f32_e32 v217, v217
	v_rcp_f32_e32 v218, v218
	v_rcp_f32_e32 v219, v219
	v_rcp_f32_e32 v220, v220
	v_rcp_f32_e32 v221, v221
	v_pk_mul_f32 v[214:215], v[206:207], v[214:215]
	v_pk_mul_f32 v[216:217], v[208:209], v[216:217]
	v_pk_mul_f32 v[218:219], v[210:211], v[218:219]
	v_pk_mul_f32 v[220:221], v[212:213], v[220:221]
	v_pk_mul_f32 v[206:207], v[86:87], v[166:167] op_sel_hi:[1,0]
	v_pk_mul_f32 v[208:209], v[88:89], v[166:167] op_sel_hi:[1,0]
	v_pk_mul_f32 v[210:211], v[82:83], v[166:167] op_sel_hi:[1,0]
	v_pk_mul_f32 v[212:213], v[84:85], v[166:167] op_sel_hi:[1,0]
	v_pk_mul_f32 v[214:215], v[206:207], v[214:215]
	v_pk_mul_f32 v[216:217], v[208:209], v[216:217]
	v_pk_mul_f32 v[218:219], v[210:211], v[218:219]
	v_pk_mul_f32 v[220:221], v[212:213], v[220:221]
	v_cvt_pk_bf16_f32 v224, v214, v215
	v_cvt_pk_bf16_f32 v225, v216, v217
	v_cvt_pk_bf16_f32 v226, v218, v219
	v_cvt_pk_bf16_f32 v227, v220, v221
	flat_store_dwordx4 v[158:159], v[224:227]
	v_mad_u64_u32 v[158:159], s[4:5], v154, s16, v[136:137]
	v_mov_b32_e32 v154, v159
	v_mad_u64_u32 v[154:155], s[4:5], v155, s16, v[154:155]
	v_mov_b32_e32 v159, v154
	v_lshl_add_u64 v[154:155], v[158:159], 0, v[138:139]
	v_pk_mul_f32 v[232:233], v[110:111], v[162:163] op_sel_hi:[1,0]
	v_pk_mul_f32 v[234:235], v[112:113], v[162:163] op_sel_hi:[1,0]
	v_pk_mul_f32 v[236:237], v[106:107], v[162:163] op_sel_hi:[1,0]
	v_pk_mul_f32 v[240:241], v[108:109], v[162:163] op_sel_hi:[1,0]
	v_pk_mul_f32 v[242:243], v[232:233], v[196:197] op_sel_hi:[1,0]
	v_pk_mul_f32 v[244:245], v[234:235], v[196:197] op_sel_hi:[1,0]
	v_pk_mul_f32 v[248:249], v[236:237], v[196:197] op_sel_hi:[1,0]
	v_pk_mul_f32 v[200:201], v[240:241], v[196:197] op_sel_hi:[1,0]
	v_exp_f32_e32 v242, v242
	v_exp_f32_e32 v243, v243
	v_exp_f32_e32 v244, v244
	v_exp_f32_e32 v245, v245
	v_exp_f32_e32 v248, v248
	v_exp_f32_e32 v249, v249
	v_exp_f32_e32 v200, v200
	v_exp_f32_e32 v201, v201
	v_pk_add_f32 v[242:243], v[242:243], 1.0 op_sel_hi:[1,0]
	v_pk_add_f32 v[244:245], v[244:245], 1.0 op_sel_hi:[1,0]
	v_pk_add_f32 v[248:249], v[248:249], 1.0 op_sel_hi:[1,0]
	v_pk_add_f32 v[200:201], v[200:201], 1.0 op_sel_hi:[1,0]
	v_rcp_f32_e32 v242, v242
	v_rcp_f32_e32 v243, v243
	v_rcp_f32_e32 v244, v244
	v_rcp_f32_e32 v245, v245
	v_rcp_f32_e32 v248, v248
	v_rcp_f32_e32 v249, v249
	v_rcp_f32_e32 v200, v200
	v_rcp_f32_e32 v201, v201
	v_pk_mul_f32 v[242:243], v[232:233], v[242:243]
	v_pk_mul_f32 v[244:245], v[234:235], v[244:245]
	v_pk_mul_f32 v[248:249], v[236:237], v[248:249]
	v_pk_mul_f32 v[200:201], v[240:241], v[200:201]
	v_pk_mul_f32 v[232:233], v[78:79], v[162:163] op_sel_hi:[1,0]
	v_pk_mul_f32 v[234:235], v[80:81], v[162:163] op_sel_hi:[1,0]
	v_pk_mul_f32 v[236:237], v[74:75], v[162:163] op_sel_hi:[1,0]
	v_pk_mul_f32 v[240:241], v[76:77], v[162:163] op_sel_hi:[1,0]
	v_pk_mul_f32 v[242:243], v[232:233], v[242:243]
	v_pk_mul_f32 v[244:245], v[234:235], v[244:245]
	v_pk_mul_f32 v[248:249], v[236:237], v[248:249]
	v_pk_mul_f32 v[200:201], v[240:241], v[200:201]
	v_cvt_pk_bf16_f32 v228, v242, v243
	v_cvt_pk_bf16_f32 v229, v244, v245
	v_cvt_pk_bf16_f32 v230, v248, v249
	v_cvt_pk_bf16_f32 v231, v200, v201
	flat_store_dwordx4 v[154:155], v[228:231]
	v_mad_u64_u32 v[154:155], s[4:5], v176, s16, v[136:137]
	v_mov_b32_e32 v158, v155
	v_mad_u64_u32 v[158:159], s[4:5], v177, s16, v[158:159]
	v_mov_b32_e32 v155, v158
	v_lshl_add_u64 v[154:155], v[154:155], 0, v[138:139]
	v_pk_mul_f32 v[206:207], v[70:71], v[160:161] op_sel_hi:[1,0]
	v_pk_mul_f32 v[208:209], v[72:73], v[160:161] op_sel_hi:[1,0]
	v_pk_mul_f32 v[210:211], v[66:67], v[160:161] op_sel_hi:[1,0]
	v_pk_mul_f32 v[212:213], v[68:69], v[160:161] op_sel_hi:[1,0]
	v_pk_mul_f32 v[214:215], v[206:207], v[196:197] op_sel_hi:[1,0]
	v_pk_mul_f32 v[216:217], v[208:209], v[196:197] op_sel_hi:[1,0]
	v_pk_mul_f32 v[218:219], v[210:211], v[196:197] op_sel_hi:[1,0]
	v_pk_mul_f32 v[220:221], v[212:213], v[196:197] op_sel_hi:[1,0]
	v_exp_f32_e32 v214, v214
	v_exp_f32_e32 v215, v215
	v_exp_f32_e32 v216, v216
	v_exp_f32_e32 v217, v217
	v_exp_f32_e32 v218, v218
	v_exp_f32_e32 v219, v219
	v_exp_f32_e32 v220, v220
	v_exp_f32_e32 v221, v221
	v_pk_add_f32 v[214:215], v[214:215], 1.0 op_sel_hi:[1,0]
	v_pk_add_f32 v[216:217], v[216:217], 1.0 op_sel_hi:[1,0]
	v_pk_add_f32 v[218:219], v[218:219], 1.0 op_sel_hi:[1,0]
	v_pk_add_f32 v[220:221], v[220:221], 1.0 op_sel_hi:[1,0]
	v_rcp_f32_e32 v214, v214
	v_rcp_f32_e32 v215, v215
	v_rcp_f32_e32 v216, v216
	v_rcp_f32_e32 v217, v217
	v_rcp_f32_e32 v218, v218
	v_rcp_f32_e32 v219, v219
	v_rcp_f32_e32 v220, v220
	v_rcp_f32_e32 v221, v221
	v_pk_mul_f32 v[214:215], v[206:207], v[214:215]
	v_pk_mul_f32 v[216:217], v[208:209], v[216:217]
	v_pk_mul_f32 v[218:219], v[210:211], v[218:219]
	v_pk_mul_f32 v[220:221], v[212:213], v[220:221]
	v_pk_mul_f32 v[206:207], v[38:39], v[160:161] op_sel_hi:[1,0]
	v_pk_mul_f32 v[208:209], v[40:41], v[160:161] op_sel_hi:[1,0]
	v_pk_mul_f32 v[210:211], v[34:35], v[160:161] op_sel_hi:[1,0]
	v_pk_mul_f32 v[212:213], v[36:37], v[160:161] op_sel_hi:[1,0]
	v_pk_mul_f32 v[214:215], v[206:207], v[214:215]
	v_pk_mul_f32 v[216:217], v[208:209], v[216:217]
	v_pk_mul_f32 v[218:219], v[210:211], v[218:219]
	v_pk_mul_f32 v[220:221], v[212:213], v[220:221]
	v_cvt_pk_bf16_f32 v224, v214, v215
	v_cvt_pk_bf16_f32 v225, v216, v217
	v_cvt_pk_bf16_f32 v226, v218, v219
	v_cvt_pk_bf16_f32 v227, v220, v221
	flat_store_dwordx4 v[154:155], v[224:227]
	v_add_u32_e32 v135, 16, v152
	v_mad_i64_i32 v[154:155], s[4:5], v135, s16, v[136:137]
	v_lshl_add_u64 v[154:155], v[154:155], 0, v[138:139]
	v_pk_mul_f32 v[232:233], v[62:63], v[156:157] op_sel_hi:[1,0]
	v_pk_mul_f32 v[234:235], v[64:65], v[156:157] op_sel_hi:[1,0]
	v_pk_mul_f32 v[236:237], v[58:59], v[156:157] op_sel_hi:[1,0]
	v_pk_mul_f32 v[240:241], v[60:61], v[156:157] op_sel_hi:[1,0]
	v_pk_mul_f32 v[242:243], v[232:233], v[196:197] op_sel_hi:[1,0]
	v_pk_mul_f32 v[244:245], v[234:235], v[196:197] op_sel_hi:[1,0]
	v_pk_mul_f32 v[248:249], v[236:237], v[196:197] op_sel_hi:[1,0]
	v_pk_mul_f32 v[200:201], v[240:241], v[196:197] op_sel_hi:[1,0]
	v_exp_f32_e32 v242, v242
	v_exp_f32_e32 v243, v243
	v_exp_f32_e32 v244, v244
	v_exp_f32_e32 v245, v245
	v_exp_f32_e32 v248, v248
	v_exp_f32_e32 v249, v249
	v_exp_f32_e32 v200, v200
	v_exp_f32_e32 v201, v201
	v_pk_add_f32 v[242:243], v[242:243], 1.0 op_sel_hi:[1,0]
	v_pk_add_f32 v[244:245], v[244:245], 1.0 op_sel_hi:[1,0]
	v_pk_add_f32 v[248:249], v[248:249], 1.0 op_sel_hi:[1,0]
	v_pk_add_f32 v[200:201], v[200:201], 1.0 op_sel_hi:[1,0]
	v_rcp_f32_e32 v242, v242
	v_rcp_f32_e32 v243, v243
	v_rcp_f32_e32 v244, v244
	v_rcp_f32_e32 v245, v245
	v_rcp_f32_e32 v248, v248
	v_rcp_f32_e32 v249, v249
	v_rcp_f32_e32 v200, v200
	v_rcp_f32_e32 v201, v201
	v_pk_mul_f32 v[242:243], v[232:233], v[242:243]
	v_pk_mul_f32 v[244:245], v[234:235], v[244:245]
	v_pk_mul_f32 v[248:249], v[236:237], v[248:249]
	v_pk_mul_f32 v[200:201], v[240:241], v[200:201]
	v_pk_mul_f32 v[232:233], v[30:31], v[156:157] op_sel_hi:[1,0]
	v_pk_mul_f32 v[234:235], v[32:33], v[156:157] op_sel_hi:[1,0]
	v_pk_mul_f32 v[236:237], v[26:27], v[156:157] op_sel_hi:[1,0]
	v_pk_mul_f32 v[240:241], v[28:29], v[156:157] op_sel_hi:[1,0]
	v_pk_mul_f32 v[242:243], v[232:233], v[242:243]
	v_pk_mul_f32 v[244:245], v[234:235], v[244:245]
	v_pk_mul_f32 v[248:249], v[236:237], v[248:249]
	v_pk_mul_f32 v[200:201], v[240:241], v[200:201]
	v_cvt_pk_bf16_f32 v228, v242, v243
	v_cvt_pk_bf16_f32 v229, v244, v245
	v_cvt_pk_bf16_f32 v230, v248, v249
	v_cvt_pk_bf16_f32 v231, v200, v201
	flat_store_dwordx4 v[154:155], v[228:231]
	v_add_u32_e32 v135, 32, v152
	v_mad_i64_i32 v[154:155], s[4:5], v135, s16, v[136:137]
	v_lshl_add_u64 v[154:155], v[154:155], 0, v[138:139]
	v_add_u32_e32 v135, 48, v152
	v_mad_i64_i32 v[136:137], s[4:5], v135, s16, v[136:137]
	v_lshl_add_u64 v[136:137], v[136:137], 0, v[138:139]
	v_pk_mul_f32 v[206:207], v[54:55], v[140:141] op_sel_hi:[1,0]
	v_pk_mul_f32 v[208:209], v[56:57], v[140:141] op_sel_hi:[1,0]
	v_pk_mul_f32 v[210:211], v[50:51], v[140:141] op_sel_hi:[1,0]
	v_pk_mul_f32 v[212:213], v[52:53], v[140:141] op_sel_hi:[1,0]
	v_pk_mul_f32 v[214:215], v[206:207], v[196:197] op_sel_hi:[1,0]
	v_pk_mul_f32 v[216:217], v[208:209], v[196:197] op_sel_hi:[1,0]
	v_pk_mul_f32 v[218:219], v[210:211], v[196:197] op_sel_hi:[1,0]
	v_pk_mul_f32 v[220:221], v[212:213], v[196:197] op_sel_hi:[1,0]
	v_exp_f32_e32 v214, v214
	v_exp_f32_e32 v215, v215
	v_exp_f32_e32 v216, v216
	v_exp_f32_e32 v217, v217
	v_exp_f32_e32 v218, v218
	v_exp_f32_e32 v219, v219
	v_exp_f32_e32 v220, v220
	v_exp_f32_e32 v221, v221
	v_pk_add_f32 v[214:215], v[214:215], 1.0 op_sel_hi:[1,0]
	v_pk_add_f32 v[216:217], v[216:217], 1.0 op_sel_hi:[1,0]
	v_pk_add_f32 v[218:219], v[218:219], 1.0 op_sel_hi:[1,0]
	v_pk_add_f32 v[220:221], v[220:221], 1.0 op_sel_hi:[1,0]
	v_rcp_f32_e32 v214, v214
	v_rcp_f32_e32 v215, v215
	v_rcp_f32_e32 v216, v216
	v_rcp_f32_e32 v217, v217
	v_rcp_f32_e32 v218, v218
	v_rcp_f32_e32 v219, v219
	v_rcp_f32_e32 v220, v220
	v_rcp_f32_e32 v221, v221
	v_pk_mul_f32 v[214:215], v[206:207], v[214:215]
	v_pk_mul_f32 v[216:217], v[208:209], v[216:217]
	v_pk_mul_f32 v[218:219], v[210:211], v[218:219]
	v_pk_mul_f32 v[220:221], v[212:213], v[220:221]
	v_pk_mul_f32 v[206:207], v[22:23], v[140:141] op_sel_hi:[1,0]
	v_pk_mul_f32 v[208:209], v[24:25], v[140:141] op_sel_hi:[1,0]
	v_pk_mul_f32 v[210:211], v[18:19], v[140:141] op_sel_hi:[1,0]
	v_pk_mul_f32 v[212:213], v[20:21], v[140:141] op_sel_hi:[1,0]
	v_pk_mul_f32 v[214:215], v[206:207], v[214:215]
	v_pk_mul_f32 v[216:217], v[208:209], v[216:217]
	v_pk_mul_f32 v[218:219], v[210:211], v[218:219]
	v_pk_mul_f32 v[220:221], v[212:213], v[220:221]
	v_cvt_pk_bf16_f32 v224, v214, v215
	v_cvt_pk_bf16_f32 v225, v216, v217
	v_cvt_pk_bf16_f32 v226, v218, v219
	v_cvt_pk_bf16_f32 v227, v220, v221
	flat_store_dwordx4 v[154:155], v[224:227]
	v_pk_mul_f32 v[232:233], v[46:47], v[134:135] op_sel_hi:[1,0]
	v_pk_mul_f32 v[234:235], v[48:49], v[134:135] op_sel_hi:[1,0]
	v_pk_mul_f32 v[236:237], v[42:43], v[134:135] op_sel_hi:[1,0]
	v_pk_mul_f32 v[240:241], v[44:45], v[134:135] op_sel_hi:[1,0]
	v_pk_mul_f32 v[242:243], v[232:233], v[196:197] op_sel_hi:[1,0]
	v_pk_mul_f32 v[244:245], v[234:235], v[196:197] op_sel_hi:[1,0]
	v_pk_mul_f32 v[248:249], v[236:237], v[196:197] op_sel_hi:[1,0]
	v_pk_mul_f32 v[200:201], v[240:241], v[196:197] op_sel_hi:[1,0]
	v_exp_f32_e32 v242, v242
	v_exp_f32_e32 v243, v243
	v_exp_f32_e32 v244, v244
	v_exp_f32_e32 v245, v245
	v_exp_f32_e32 v248, v248
	v_exp_f32_e32 v249, v249
	v_exp_f32_e32 v200, v200
	v_exp_f32_e32 v201, v201
	v_pk_add_f32 v[242:243], v[242:243], 1.0 op_sel_hi:[1,0]
	v_pk_add_f32 v[244:245], v[244:245], 1.0 op_sel_hi:[1,0]
	v_pk_add_f32 v[248:249], v[248:249], 1.0 op_sel_hi:[1,0]
	v_pk_add_f32 v[200:201], v[200:201], 1.0 op_sel_hi:[1,0]
	v_rcp_f32_e32 v242, v242
	v_rcp_f32_e32 v243, v243
	v_rcp_f32_e32 v244, v244
	v_rcp_f32_e32 v245, v245
	v_rcp_f32_e32 v248, v248
	v_rcp_f32_e32 v249, v249
	v_rcp_f32_e32 v200, v200
	v_rcp_f32_e32 v201, v201
	v_pk_mul_f32 v[242:243], v[232:233], v[242:243]
	v_pk_mul_f32 v[244:245], v[234:235], v[244:245]
	v_pk_mul_f32 v[248:249], v[236:237], v[248:249]
	v_pk_mul_f32 v[200:201], v[240:241], v[200:201]
	v_pk_mul_f32 v[232:233], v[10:11], v[134:135] op_sel_hi:[1,0]
	v_pk_mul_f32 v[234:235], v[12:13], v[134:135] op_sel_hi:[1,0]
	v_pk_mul_f32 v[236:237], v[2:3], v[134:135] op_sel_hi:[1,0]
	v_pk_mul_f32 v[240:241], v[4:5], v[134:135] op_sel_hi:[1,0]
	v_pk_mul_f32 v[242:243], v[232:233], v[242:243]
	v_pk_mul_f32 v[244:245], v[234:235], v[244:245]
	v_pk_mul_f32 v[248:249], v[236:237], v[248:249]
	v_pk_mul_f32 v[200:201], v[240:241], v[200:201]
	v_cvt_pk_bf16_f32 v228, v242, v243
	v_cvt_pk_bf16_f32 v229, v244, v245
	v_cvt_pk_bf16_f32 v230, v248, v249
	v_cvt_pk_bf16_f32 v231, v200, v201
	flat_store_dwordx4 v[136:137], v[228:231]
	s_cbranch_vccnz .LBB0_607
	s_waitcnt vmcnt(0)
	s_and_saveexec_b64 s[4:5], s[0:1]
	s_cbranch_execz .LBB0_606
	s_lshl_b32 s16, s18, 4
	s_ashr_i32 s17, s16, 31
	s_lshl_b64 s[16:17], s[16:17], 2
	s_add_u32 s16, s66, s16
	s_addc_u32 s17, s67, s17
	v_mov_b64_e32 v[134:135], s[16:17]
	s_waitcnt vmcnt(0)
	flat_atomic_add v[134:135], v198
